# P0: waves 4-7 convert weights first and stream their residual rows afterwards (waves 0-3 keep the order), on top of the batched W_in transpose loads
# speedup vs baseline: 1.0096x; 1.0096x over previous
; #define LAS __attribute__((address_space(3)))
; __device__ __forceinline__ int opaque_tid(int wv) { int t = wv * 64 + (int)__builtin_amdgcn_mbcnt_hi(~0u, __builtin_amdgcn_mbcnt_lo(~0u, 0u)); asm volatile("" : "+v"(t)); return t; }
; __device__ __forceinline__ void phase_init(const Args& a, LAS unsigned char* lds, int vcu, int NGW, int wv) {
;     const int tid = opaque_tid(wv), lane = tid & 63, wave = __builtin_amdgcn_readfirstlane(tid >> 6), gw = vcu * 8 + wave;
;     bf16_t* H = (bf16_t*)(a.ws + WS_H); float* metah = (float*)(a.ws + WS_METAH); float* rope = (float*)(a.ws + WS_ROPE);
;     for (int m0 = gw; m0 < MP; m0 += 2 * NGW) {
;         f32x4 v[2][4]; const float* srcs[2];
; #pragma unroll
;         for (int k = 0; k < 2; ++k) { const int m = m0 + k * NGW; srcs[k] = nullptr;
;             if (m < MP) { const int b = m / LP, t = m - b * LP - PADF;
.Lp0s_rows:
	v_mov_b32_e32 v17, v228
	s_nop 0
	v_readfirstlane_b32 s0, v17
	s_ashr_i32 s8, s0, 6
	v_readlane_b32 s0, v254, 17
	s_add_i32 s9, s8, s0
	v_and_b32_e32 v14, 63, v17
	s_cmp_lt_i32 s9, 0x8200
	s_mov_b64 s[0:1], -1
	s_cbranch_scc1 .LBB0_739
	v_mov_b32_e32 v15, v1
	s_mov_b64 s[0:1], 0
.LBB0_739:
	v_readlane_b32 s2, v255, 62
	s_nop 3
	s_cmp_lg_u32 s2, 0
	s_cbranch_scc1 .Lp0s_739_done
	s_cmp_lt_i32 s8, 4
	s_cbranch_scc1 .Lp0s_739_done
	s_mov_b32 s2, 1
	s_nop 0
	v_writelane_b32 v255, s2, 62
	v_mov_b32_e32 v15, v1
	s_mov_b64 s[0:1], 0

; __device__ __forceinline__ int opaque_tid(int wv) { int t = wv * 64 + (int)__builtin_amdgcn_mbcnt_hi(~0u, __builtin_amdgcn_mbcnt_lo(~0u, 0u)); asm volatile("" : "+v"(t)); return t; }
; __device__ __forceinline__ void phase_init(const Args& a, LAS unsigned char* lds, int vcu, int NGW, int wv) {
;     ...
;     for (int m0 = gw; m0 < MP; m0 += 2 * NGW) {
; __global__ void __launch_bounds__(512, 2) trunk_fwd(Args a0) {
;     ...
;         if (ph + 1 < a0.ph_hi) { if (ph == 0) { __syncthreads(); cg::this_grid().sync(); } else xcd_barrier(bar, opaque_tid(wv)); }
.LBB0_817:
	v_readlane_b32 s2, v255, 62
	s_nop 3
	s_cmp_eq_u32 s2, 1
	s_cbranch_scc0 .Lp0s_817_a
	s_mov_b32 s2, 2
	s_nop 0
	v_writelane_b32 v255, s2, 62
	s_branch .Lp0s_rows
